# XCD-local barriers disabled (placement check forced to mismatch, every seam uses the hierarchical global barrier); tests the fallback path
# baseline (speedup 1.0000x reference)
; DI int half_() { return __builtin_amdgcn_readfirstlane((int)(threadIdx.x >> 8)); }
; DI void grid_barrier(unsigned* bar, unsigned gen) {
;   asm volatile("s_waitcnt vmcnt(0)" ::: "memory");
;   __syncthreads();
;   if (threadIdx.x == 0) {
;     __builtin_amdgcn_fence(__ATOMIC_RELEASE, "agent");
;     const unsigned grp = blockIdx.x & 15u;
;     const unsigned nblk = (gridDim.x + 15u - grp) >> 4;
;     unsigned old = __hip_atomic_fetch_add(bar + 64 * (1 + grp), 1u, __ATOMIC_RELAXED, __HIP_MEMORY_SCOPE_AGENT);
; __global__ void __launch_bounds__(512, 2) mega(Params p_unused, int ph0, int ph1) {
;   __shared__ __attribute__((aligned(16))) unsigned char lds_all[LDS_BYTES];
;   unsigned char* ldsb = lds_all + half_() * LDS_HALF;
;   cg::grid_group grid = cg::this_grid();
;   for (int ph = ph0; ph < ph1; ++ph) {
;     const __attribute__((address_space(4))) Params* pp = (const __attribute__((address_space(4))) Params*)__builtin_amdgcn_kernarg_segment_ptr();
;     asm volatile("" : "+s"(pp));
;     PREF p = *pp;
;     if (ph1 < 0) grid.sync();
;     if (ph > ph0) grid_barrier(p.bar, (unsigned)(ph - ph0));
;     if (ph == 0) { run_phase<9>(p, 0, ldsb, lds_all); continue; }
;     int l = (ph - 1) / NPH_LAYER; const int j = (ph - 1) % NPH_LAYER;
;     asm volatile("" : "+s"(l));
.LBB0_1:
	s_lshr_b32 s33, s0, 8
	v_readlane_b32 s0, v254, 1
	v_readlane_b32 s1, v254, 2
	s_add_u32 s2, s0, 0x1a8
	s_addc_u32 s3, s1, 0
	v_writelane_b32 v254, s2, 5
	v_lshrrev_b32_e32 v1, 20, v0
	v_lshrrev_b32_e32 v0, 10, v0
	v_writelane_b32 v254, s3, 6
	v_or_b32_e32 v0, v0, v1
	s_movk_i32 s2, 0x3ff
	v_and_or_b32 v0, v0, s2, v168
	v_readlane_b32 s8, v254, 3
	v_cmp_eq_u32_e64 s[2:3], 0, v0
	v_readlane_b32 s9, v254, 4
	s_load_dword s5, s[0:1], 0x1a8
	v_writelane_b32 v254, s2, 7
	s_cmp_lt_i32 s9, 0
	s_cselect_b64 s[0:1], -1, 0
	v_writelane_b32 v254, s3, 8
	v_cmp_eq_u32_e64 s[2:3], 0, v168
	s_waitcnt lgkmcnt(0)
	s_lshr_b32 s45, s5, 3
	s_mul_i32 s33, s33, 0x12400
	v_writelane_b32 v254, s2, 9
	v_cndmask_b32_e64 v0, 0, 1, s[0:1]
	v_cmp_ne_u32_e64 s[0:1], 1, v0
	v_writelane_b32 v254, s3, 10
	v_mbcnt_lo_u32_b32 v0, -1, 0
	v_readlane_b32 s4, v254, 0
	s_and_b32 s2, s4, 15
	s_xor_b32 s3, s2, 15
	s_add_i32 s3, s5, s3
	s_lshr_b32 s3, s3, 4
	s_lshl_b32 s2, s2, 6
	s_lshr_b32 s46, s4, 3
	s_cmpk_lt_u32 s4, 0x200
	v_writelane_b32 v254, s3, 11
	s_cselect_b64 s[6:7], -1, 0
	s_lshl_b32 s3, s4, 4
	s_and_b32 s47, s3, 0x70
	s_lshl_b32 s3, s4, 3
	s_lshl_b32 s48, s5, 3
	v_writelane_b32 v254, s6, 12
	s_cmpk_lt_i32 s4, 0x100
	s_mov_b32 s53, 0
	v_writelane_b32 v254, s7, 13
	s_cselect_b64 s[6:7], -1, 0
	v_writelane_b32 v254, s6, 14
	s_ashr_i32 s49, s48, 31
	s_lshl_b32 s64, s5, 9
	v_writelane_b32 v254, s7, 15
	s_add_i32 s6, s33, 0x12000
	v_writelane_b32 v254, s6, 16
	s_lshl_b32 s6, s4, 9
	v_writelane_b32 v254, s6, 17
	s_lshl_b64 s[6:7], s[48:49], 11
	v_writelane_b32 v254, s6, 18
	s_ashr_i32 s65, s64, 31
	s_lshl_b32 s70, s4, 1
	v_writelane_b32 v254, s7, 19
	v_writelane_b32 v254, s3, 20
	s_addk_i32 s3, 0x4000
	v_writelane_b32 v254, s3, 21
	s_lshl_b32 s3, s4, 8
	v_writelane_b32 v254, s3, 22
	s_lshl_b32 s3, s5, 8
	v_writelane_b32 v254, s3, 23
	s_add_i32 s3, s33, 0x4000
	v_writelane_b32 v254, s3, 24
	s_lshl_b32 s3, s4, 6
	v_writelane_b32 v254, s3, 25
	s_lshl_b64 s[6:7], s[64:65], 4
	v_writelane_b32 v254, s6, 26
	s_lshl_b32 s3, s5, 10
	s_lshl_b32 s71, s5, 1
	v_writelane_b32 v254, s7, 27
	s_lshl_b64 s[6:7], s[64:65], 5
	v_writelane_b32 v254, s6, 28
	s_lshl_b32 s81, s4, 7
	s_lshl_b32 s84, s5, 7
	v_writelane_b32 v254, s7, 29
	s_lshl_b64 s[6:7], s[48:49], 12
	v_writelane_b32 v254, s6, 30
	s_lshl_b32 s85, s5, 6
	s_movk_i32 s66, 0x200
	v_writelane_b32 v254, s7, 31
	v_writelane_b32 v254, s5, 32
	v_writelane_b32 v254, s3, 33
	s_lshl_b64 s[4:5], s[64:65], 2
	v_writelane_b32 v254, s4, 34
	v_and_b32_e32 v169, 0xff, v168
	s_movk_i32 s67, 0x100
	v_writelane_b32 v254, s5, 35
	v_writelane_b32 v254, s0, 36
	s_lshl_b64 s[72:73], s[64:65], 6
	v_mov_b32_e32 v1, 0
	v_writelane_b32 v254, s1, 37
	s_lshl_b32 s0, s2, 2
	v_writelane_b32 v254, s0, 38
	v_writelane_b32 v254, s45, 39
	v_writelane_b32 v254, s46, 40
	v_writelane_b32 v254, s47, 41
	s_mov_b32 s0, s48
	v_writelane_b32 v254, s0, 42
	s_mov_b32 s88, 0x10000
	v_mov_b32_e32 v170, 0x1000
	v_writelane_b32 v254, s1, 43
	s_mov_b32 s0, s64
	s_mov_b64 s[76:77], 0x80
	s_mov_b64 s[78:79], 0x40080
	s_mov_b64 s[42:43], 0x12b0100
	s_mov_b64 s[82:83], 0x100
	s_mov_b64 s[86:87], 0x40100
	s_mov_b64 s[90:91], 0x180
	s_movk_i32 s89, 0x180
	s_movk_i32 s92, 0x210
	s_movk_i32 s93, 0x80
	v_mov_b32_e32 v171, 0x3727c5ac
	s_mov_b32 s61, 0x800000
	s_movk_i32 s80, 0x1000
	s_mov_b64 s[50:51], 0x580100
	s_mov_b64 s[38:39], 0x980100
	s_mov_b64 s[4:5], 0x580180
	s_mov_b64 s[74:75], 0x980180
	s_movk_i32 s60, 0x1540
	s_movk_i32 s96, 0x300
	s_movk_i32 s97, 0x90
	s_mov_b32 s94, 0xff800000
	v_mbcnt_hi_u32_b32 v172, -1, v0
	v_mov_b32_e32 v163, 1.0
	s_mov_b64 s[2:3], 0xaa000
	v_mov_b32_e32 v173, 0x358637bd
	s_movk_i32 s95, 0x400
	s_mov_b64 s[6:7], 0x40180
	s_movk_i32 s58, 0xaa0
	s_movk_i32 s59, 0x600
	s_movk_i32 s54, 0x2a80
	v_mov_b32_e32 v174, 0x3c0881c4
	v_mov_b32_e32 v175, 0xbab64f3b
	v_mov_b32_e32 v176, 0xff800000
	v_mov_b32_e32 v177, 0x7f800000
	v_not_b32_e32 v178, 63
	v_not_b32_e32 v179, 31
	v_mov_b32_e32 v180, 0x7fc00000
	v_mov_b32_e32 v181, 0x37000000
	s_mov_b32 s34, s8
	v_writelane_b32 v254, s0, 44
	s_nop 1
	v_writelane_b32 v254, s1, 45
	s_getreg_b32 s0, hwreg(HW_REG_XCC_ID, 0, 4)
	v_writelane_b32 v254, s0, 61
	s_mov_b32 s1, 0
	v_writelane_b32 v254, s1, 62
	v_writelane_b32 v254, s1, 63
	v_writelane_b32 v254, s1, 60
	s_nop 0
	v_readlane_b32 s1, v254, 0
	s_and_b32 s1, s1, 7
	s_xor_b32 s1, s1, 1
	s_cmp_lg_u32 s0, s1
	s_cselect_b32 s1, 0x10001, 1
	v_readlane_b32 s12, v254, 9
	v_readlane_b32 s13, v254, 10
	s_and_saveexec_b64 s[14:15], s[12:13]
	s_cbranch_execz .Lmy_xb_posted
	v_readlane_b32 s12, v254, 1
	v_readlane_b32 s13, v254, 2
	s_load_dwordx2 s[12:13], s[12:13], 0x198
	s_lshl_b32 s0, s0, 8
	s_addk_i32 s0, 0x400
	v_mov_b32_e32 v0, s0
	v_mov_b32_e32 v2, s1
	s_waitcnt lgkmcnt(0)
	global_atomic_add v0, v2, s[12:13]
